# code placement: the four GEMM K-loop heads pinned to 8-byte alignment (.p2align 3)
# speedup vs baseline: 1.0073x; 1.0073x over previous
.LBB0_45:
	s_andn2_b64 vcc, exec, s[14:15]
	v_mov_b64_e32 v[0:1], 0
	v_mov_b64_e32 v[2:3], 0
	v_mov_b64_e32 v[4:5], 0
	v_mov_b64_e32 v[6:7], 0
	v_mov_b64_e32 v[8:9], 0
	v_mov_b64_e32 v[10:11], 0
	v_mov_b64_e32 v[12:13], 0
	v_mov_b64_e32 v[14:15], 0
	v_mov_b64_e32 v[16:17], 0
	v_mov_b64_e32 v[18:19], 0
	v_mov_b64_e32 v[20:21], 0
	v_mov_b64_e32 v[22:23], 0
	v_mov_b64_e32 v[24:25], 0
	v_mov_b64_e32 v[26:27], 0
	v_mov_b64_e32 v[28:29], 0
	v_mov_b64_e32 v[30:31], 0
	v_mov_b64_e32 v[32:33], 0
	v_mov_b64_e32 v[34:35], 0
	v_mov_b64_e32 v[36:37], 0
	v_mov_b64_e32 v[38:39], 0
	v_mov_b64_e32 v[40:41], 0
	v_mov_b64_e32 v[42:43], 0
	v_mov_b64_e32 v[44:45], 0
	v_mov_b64_e32 v[46:47], 0
	v_mov_b64_e32 v[48:49], 0
	v_mov_b64_e32 v[50:51], 0
	v_mov_b64_e32 v[52:53], 0
	v_mov_b64_e32 v[54:55], 0
	v_mov_b64_e32 v[56:57], 0
	v_mov_b64_e32 v[58:59], 0
	v_mov_b64_e32 v[60:61], 0
	v_mov_b64_e32 v[62:63], 0
	v_mov_b64_e32 v[64:65], 0
	v_mov_b64_e32 v[66:67], 0
	v_mov_b64_e32 v[68:69], 0
	v_mov_b64_e32 v[70:71], 0
	v_mov_b64_e32 v[72:73], 0
	v_mov_b64_e32 v[74:75], 0
	v_mov_b64_e32 v[76:77], 0
	v_mov_b64_e32 v[78:79], 0
	v_mov_b64_e32 v[80:81], 0
	v_mov_b64_e32 v[82:83], 0
	v_mov_b64_e32 v[84:85], 0
	v_mov_b64_e32 v[86:87], 0
	v_mov_b64_e32 v[88:89], 0
	v_mov_b64_e32 v[90:91], 0
	v_mov_b64_e32 v[92:93], 0
	v_mov_b64_e32 v[94:95], 0
	v_mov_b64_e32 v[96:97], 0
	v_mov_b64_e32 v[98:99], 0
	v_mov_b64_e32 v[100:101], 0
	v_mov_b64_e32 v[102:103], 0
	v_mov_b64_e32 v[104:105], 0
	v_mov_b64_e32 v[106:107], 0
	v_mov_b64_e32 v[108:109], 0
	v_mov_b64_e32 v[110:111], 0
	v_mov_b64_e32 v[112:113], 0
	v_mov_b64_e32 v[114:115], 0
	v_mov_b64_e32 v[116:117], 0
	v_mov_b64_e32 v[118:119], 0
	v_mov_b64_e32 v[120:121], 0
	v_mov_b64_e32 v[122:123], 0
	v_mov_b64_e32 v[124:125], 0
	v_mov_b64_e32 v[126:127], 0
	s_cbranch_vccnz .LBB0_49
	s_add_u32 s0, s28, 0x80
	s_addc_u32 s1, s29, 0
	s_add_u32 s28, s26, 0x100
	s_addc_u32 s29, s27, 0
	s_mov_b32 s26, 0
	.p2align	3

.LBB0_101:
	s_andn2_b64 vcc, exec, s[14:15]
	v_mov_b64_e32 v[0:1], 0
	v_mov_b64_e32 v[2:3], 0
	v_mov_b64_e32 v[4:5], 0
	v_mov_b64_e32 v[6:7], 0
	v_mov_b64_e32 v[8:9], 0
	v_mov_b64_e32 v[10:11], 0
	v_mov_b64_e32 v[12:13], 0
	v_mov_b64_e32 v[14:15], 0
	v_mov_b64_e32 v[16:17], 0
	v_mov_b64_e32 v[18:19], 0
	v_mov_b64_e32 v[20:21], 0
	v_mov_b64_e32 v[22:23], 0
	v_mov_b64_e32 v[24:25], 0
	v_mov_b64_e32 v[26:27], 0
	v_mov_b64_e32 v[28:29], 0
	v_mov_b64_e32 v[30:31], 0
	v_mov_b64_e32 v[32:33], 0
	v_mov_b64_e32 v[34:35], 0
	v_mov_b64_e32 v[36:37], 0
	v_mov_b64_e32 v[38:39], 0
	v_mov_b64_e32 v[40:41], 0
	v_mov_b64_e32 v[42:43], 0
	v_mov_b64_e32 v[44:45], 0
	v_mov_b64_e32 v[46:47], 0
	v_mov_b64_e32 v[48:49], 0
	v_mov_b64_e32 v[50:51], 0
	v_mov_b64_e32 v[52:53], 0
	v_mov_b64_e32 v[54:55], 0
	v_mov_b64_e32 v[56:57], 0
	v_mov_b64_e32 v[58:59], 0
	v_mov_b64_e32 v[60:61], 0
	v_mov_b64_e32 v[62:63], 0
	v_mov_b64_e32 v[64:65], 0
	v_mov_b64_e32 v[66:67], 0
	v_mov_b64_e32 v[68:69], 0
	v_mov_b64_e32 v[70:71], 0
	v_mov_b64_e32 v[72:73], 0
	v_mov_b64_e32 v[74:75], 0
	v_mov_b64_e32 v[76:77], 0
	v_mov_b64_e32 v[78:79], 0
	v_mov_b64_e32 v[80:81], 0
	v_mov_b64_e32 v[82:83], 0
	v_mov_b64_e32 v[84:85], 0
	v_mov_b64_e32 v[86:87], 0
	v_mov_b64_e32 v[88:89], 0
	v_mov_b64_e32 v[90:91], 0
	v_mov_b64_e32 v[92:93], 0
	v_mov_b64_e32 v[94:95], 0
	v_mov_b64_e32 v[96:97], 0
	v_mov_b64_e32 v[98:99], 0
	v_mov_b64_e32 v[100:101], 0
	v_mov_b64_e32 v[102:103], 0
	v_mov_b64_e32 v[104:105], 0
	v_mov_b64_e32 v[106:107], 0
	v_mov_b64_e32 v[108:109], 0
	v_mov_b64_e32 v[110:111], 0
	v_mov_b64_e32 v[112:113], 0
	v_mov_b64_e32 v[114:115], 0
	v_mov_b64_e32 v[116:117], 0
	v_mov_b64_e32 v[118:119], 0
	v_mov_b64_e32 v[120:121], 0
	v_mov_b64_e32 v[122:123], 0
	v_mov_b64_e32 v[124:125], 0
	v_mov_b64_e32 v[126:127], 0
	s_cbranch_vccnz .LBB0_105
	s_add_u32 s24, s24, 0x80
	s_addc_u32 s25, s25, 0
	s_add_u32 s54, s26, 0x100
	s_addc_u32 s55, s27, 0
	s_mov_b32 s26, 0
	.p2align	3
